# adds MLA attention loop: 4-deep K fragment prefetch in QK^T and per-MFMA counted LDS waits in P.V
# speedup vs baseline: 1.0034x; 1.0034x over previous
.LBB0_635:
	v_lshl_add_u64 v[66:67], s[10:11], 0, v[184:185]
	v_lshl_add_u64 v[68:69], s[10:11], 0, v[186:187]
	global_load_dwordx4 v[162:165], v[66:67], off
	global_load_dwordx4 v[154:157], v[68:69], off
	v_lshl_add_u64 v[66:67], s[10:11], 0, v[178:179]
	v_lshl_add_u64 v[68:69], s[10:11], 0, v[180:181]
	global_load_dwordx4 v[158:161], v[66:67], off
	global_load_dwordx4 v[146:149], v[68:69], off
	v_lshl_add_u64 v[66:67], s[10:11], 0, v[182:183]
	global_load_dwordx4 v[150:153], v[66:67], off
	s_and_b32 s19, s17, 1
	s_setprio 1
	s_mul_i32 s6, s19, 0x6000
	v_add_u32_e32 v212, s6, v213
	v_add_u32_e32 v236, v212, v230
	v_add_u32_e32 v70, v212, v229
	ds_read_b128 v[232:235], v236 offset:32768
	ds_read_b128 v[242:245], v236 offset:45056
	ds_read_b128 v[246:249], v70 offset:32768
	ds_read_b128 v[250:253], v70 offset:45056
	s_waitcnt vmcnt(16) lgkmcnt(3)
	v_mfma_f32_32x32x16_bf16 v[82:97], v[232:235], v[142:145], 0
	v_add_u32_e32 v236, v212, v228
	ds_read_b128 v[232:235], v236 offset:32768
	s_waitcnt lgkmcnt(3)
	v_mfma_f32_32x32x16_bf16 v[66:81], v[242:245], v[142:145], 0
	ds_read_b128 v[242:245], v236 offset:45056
	s_waitcnt vmcnt(15) lgkmcnt(3)
	v_mfma_f32_32x32x16_bf16 v[82:97], v[246:249], v[138:141], v[82:97]
	v_add_u32_e32 v236, v212, v226
	ds_read_b128 v[246:249], v236 offset:32768
	s_waitcnt lgkmcnt(3)
	v_mfma_f32_32x32x16_bf16 v[66:81], v[250:253], v[138:141], v[66:81]
	ds_read_b128 v[250:253], v236 offset:45056
	s_waitcnt vmcnt(14) lgkmcnt(3)
	v_mfma_f32_32x32x16_bf16 v[82:97], v[232:235], v[134:137], v[82:97]
	v_add_u32_e32 v236, v212, v222
	ds_read_b128 v[232:235], v236 offset:32768
	s_waitcnt lgkmcnt(3)
	v_mfma_f32_32x32x16_bf16 v[66:81], v[242:245], v[134:137], v[66:81]
	ds_read_b128 v[242:245], v236 offset:45056
	s_waitcnt vmcnt(13) lgkmcnt(3)
	v_mfma_f32_32x32x16_bf16 v[82:97], v[246:249], v[130:133], v[82:97]
	v_add_u32_e32 v236, v212, v220
	ds_read_b128 v[246:249], v236 offset:32768
	s_waitcnt lgkmcnt(3)
	v_mfma_f32_32x32x16_bf16 v[66:81], v[250:253], v[130:133], v[66:81]
	ds_read_b128 v[250:253], v236 offset:45056
	s_waitcnt vmcnt(12) lgkmcnt(3)
	v_mfma_f32_32x32x16_bf16 v[82:97], v[232:235], v[126:129], v[82:97]
	v_add_u32_e32 v236, v212, v219
	ds_read_b128 v[232:235], v236 offset:32768
	s_waitcnt lgkmcnt(3)
	v_mfma_f32_32x32x16_bf16 v[66:81], v[242:245], v[126:129], v[66:81]
	ds_read_b128 v[242:245], v236 offset:45056
	s_waitcnt vmcnt(11) lgkmcnt(3)
	v_mfma_f32_32x32x16_bf16 v[82:97], v[246:249], v[122:125], v[82:97]
	v_add_u32_e32 v236, v212, v218
	ds_read_b128 v[246:249], v236 offset:32768
	s_waitcnt lgkmcnt(3)
	v_mfma_f32_32x32x16_bf16 v[66:81], v[250:253], v[122:125], v[66:81]
	ds_read_b128 v[250:253], v236 offset:45056
	s_waitcnt vmcnt(10) lgkmcnt(3)
	v_mfma_f32_32x32x16_bf16 v[82:97], v[232:235], v[118:121], v[82:97]
	v_add_u32_e32 v236, v212, v217
	ds_read_b128 v[232:235], v236 offset:32768
	s_waitcnt lgkmcnt(3)
	v_mfma_f32_32x32x16_bf16 v[66:81], v[242:245], v[118:121], v[66:81]
	ds_read_b128 v[242:245], v236 offset:45056
	s_waitcnt vmcnt(9) lgkmcnt(3)
	v_mfma_f32_32x32x16_bf16 v[82:97], v[246:249], v[114:117], v[82:97]
	v_add_u32_e32 v236, v212, v216
	ds_read_b128 v[246:249], v236 offset:32768
	s_waitcnt lgkmcnt(3)
	v_mfma_f32_32x32x16_bf16 v[66:81], v[250:253], v[114:117], v[66:81]
	ds_read_b128 v[250:253], v236 offset:45056
	s_waitcnt vmcnt(8) lgkmcnt(3)
	v_mfma_f32_32x32x16_bf16 v[82:97], v[232:235], v[110:113], v[82:97]
	v_add_u32_e32 v236, v212, v215
	ds_read_b128 v[232:235], v236 offset:32768
	s_waitcnt lgkmcnt(3)
	v_mfma_f32_32x32x16_bf16 v[66:81], v[242:245], v[110:113], v[66:81]
	ds_read_b128 v[242:245], v236 offset:45056
	s_waitcnt vmcnt(7) lgkmcnt(3)
	v_mfma_f32_32x32x16_bf16 v[82:97], v[246:249], v[106:109], v[82:97]
	v_add_u32_e32 v212, v212, v214
	ds_read_b128 v[246:249], v212 offset:32768
	s_waitcnt lgkmcnt(3)
	v_mfma_f32_32x32x16_bf16 v[66:81], v[250:253], v[106:109], v[66:81]
	ds_read_b128 v[250:253], v212 offset:45056
	s_waitcnt vmcnt(6) lgkmcnt(3)
	v_mfma_f32_32x32x16_bf16 v[82:97], v[232:235], v[102:105], v[82:97]
	s_waitcnt lgkmcnt(2)
	v_mfma_f32_32x32x16_bf16 v[66:81], v[242:245], v[102:105], v[66:81]
	s_waitcnt vmcnt(5) lgkmcnt(1)
	v_mfma_f32_32x32x16_bf16 v[82:97], v[246:249], v[98:101], v[82:97]
	s_waitcnt lgkmcnt(0)
	v_mfma_f32_32x32x16_bf16 v[66:81], v[250:253], v[98:101], v[66:81]
	s_setprio 0
	s_nop 7
	v_max_f32_e32 v212, v83, v83
	v_max_f32_e32 v232, v82, v82
	v_max_f32_e32 v212, v232, v212
	v_max3_f32 v212, v212, v84, v85
	v_max3_f32 v212, v212, v86, v87
	v_max3_f32 v212, v212, v88, v89
	v_max3_f32 v212, v212, v90, v91
	v_max3_f32 v212, v212, v92, v93
	v_max3_f32 v212, v212, v94, v95
	v_max3_f32 v212, v212, v96, v97
	v_max3_f32 v212, v212, v66, v67
	v_max3_f32 v212, v212, v68, v69
	v_max3_f32 v212, v212, v70, v71
	v_max3_f32 v212, v212, v72, v73
	v_max3_f32 v212, v212, v74, v75
	v_max3_f32 v212, v212, v76, v77
	v_max3_f32 v212, v212, v78, v79
	v_max3_f32 v212, v212, v80, v81
	v_mov_b32_e32 v232, v212
	s_nop 1
	v_permlane32_swap_b32_e32 v212, v232
	v_max_f32_e32 v232, v232, v232
	v_max_f32_e32 v212, v212, v212
	v_max_f32_e32 v212, v212, v232
	v_sub_f32_e32 v232, v212, v211
	v_cmp_ge_f32_e32 vcc, s41, v232
	v_max_f32_e32 v232, v211, v211
	v_max_f32_e32 v212, v232, v212
	v_sub_f32_e32 v232, v211, v212
	v_mul_f32_e32 v232, 0x3dd53b94, v232
	v_exp_f32_e32 v232, v232
	s_cmp_eq_u64 vcc, exec
	s_cselect_b64 s[6:7], -1, 0
	v_cndmask_b32_e64 v232, v232, 1.0, s[6:7]
	v_cmp_gt_f32_e32 vcc, 1.0, v232
	s_cbranch_vccz .LBB0_639
	s_and_saveexec_b64 s[12:13], s[4:5]
	ds_write_b32 v209, v232 offset:128
	s_or_b64 exec, exec, s[12:13]
	s_waitcnt lgkmcnt(0)
	v_add_u32_e32 v233, v208, v166
	ds_read_b128 v[234:237], v233 offset:224
	ds_read_b128 v[242:245], v233 offset:192
	ds_read_b128 v[246:249], v233 offset:160
	ds_read_b128 v[250:253], v233 offset:128
	s_waitcnt lgkmcnt(3)
	v_pk_mul_f32 v[14:15], v[14:15], v[234:235]
	s_waitcnt lgkmcnt(2)
	v_pk_mul_f32 v[10:11], v[10:11], v[242:243]
	s_waitcnt lgkmcnt(1)
	v_pk_mul_f32 v[6:7], v[6:7], v[246:247]
	v_pk_mul_f32 v[16:17], v[16:17], v[236:237]
	v_pk_mul_f32 v[12:13], v[12:13], v[244:245]
	v_pk_mul_f32 v[8:9], v[8:9], v[248:249]
	s_waitcnt lgkmcnt(0)
	v_pk_mul_f32 v[4:5], v[4:5], v[252:253]
	v_pk_mul_f32 v[2:3], v[2:3], v[250:251]
	v_pk_mul_f32 v[62:63], v[62:63], v[234:235]
	v_pk_mul_f32 v[58:59], v[58:59], v[242:243]
	v_pk_mul_f32 v[54:55], v[54:55], v[246:247]
	v_pk_mul_f32 v[64:65], v[64:65], v[236:237]
	v_pk_mul_f32 v[60:61], v[60:61], v[244:245]
	v_pk_mul_f32 v[56:57], v[56:57], v[248:249]
	v_pk_mul_f32 v[52:53], v[52:53], v[252:253]
	v_pk_mul_f32 v[50:51], v[50:51], v[250:251]
	v_pk_mul_f32 v[46:47], v[46:47], v[234:235]
	v_pk_mul_f32 v[42:43], v[42:43], v[242:243]
	v_pk_mul_f32 v[38:39], v[38:39], v[246:247]
	v_pk_mul_f32 v[48:49], v[48:49], v[236:237]
	v_pk_mul_f32 v[44:45], v[44:45], v[244:245]
	v_pk_mul_f32 v[40:41], v[40:41], v[248:249]
	v_pk_mul_f32 v[36:37], v[36:37], v[252:253]
	v_pk_mul_f32 v[34:35], v[34:35], v[250:251]
	v_pk_mul_f32 v[30:31], v[30:31], v[234:235]
	v_pk_mul_f32 v[26:27], v[26:27], v[242:243]
	v_pk_mul_f32 v[22:23], v[22:23], v[246:247]
	v_pk_mul_f32 v[32:33], v[32:33], v[236:237]
	v_pk_mul_f32 v[28:29], v[28:29], v[244:245]
	v_pk_mul_f32 v[24:25], v[24:25], v[248:249]
	v_pk_mul_f32 v[20:21], v[20:21], v[252:253]
	v_pk_mul_f32 v[18:19], v[18:19], v[250:251]
.LBB0_639:
	v_cndmask_b32_e64 v211, v212, v211, s[6:7]
	v_mul_f32_e32 v212, 0xbdd53b94, v211
	v_fmamk_f32 v82, v82, 0x3dd53b94, v212
	v_fmamk_f32 v83, v83, 0x3dd53b94, v212
	v_fmamk_f32 v84, v84, 0x3dd53b94, v212
	v_fmamk_f32 v85, v85, 0x3dd53b94, v212
	v_fmamk_f32 v86, v86, 0x3dd53b94, v212
	v_fmamk_f32 v87, v87, 0x3dd53b94, v212
	v_fmamk_f32 v88, v88, 0x3dd53b94, v212
	v_fmamk_f32 v89, v89, 0x3dd53b94, v212
	v_fmamk_f32 v90, v90, 0x3dd53b94, v212
	v_fmamk_f32 v91, v91, 0x3dd53b94, v212
	v_fmamk_f32 v92, v92, 0x3dd53b94, v212
	v_fmamk_f32 v93, v93, 0x3dd53b94, v212
	v_fmamk_f32 v94, v94, 0x3dd53b94, v212
	v_fmamk_f32 v95, v95, 0x3dd53b94, v212
	v_fmamk_f32 v96, v96, 0x3dd53b94, v212
	v_fmamk_f32 v97, v97, 0x3dd53b94, v212
	v_fmamk_f32 v66, v66, 0x3dd53b94, v212
	v_fmamk_f32 v67, v67, 0x3dd53b94, v212
	v_fmamk_f32 v68, v68, 0x3dd53b94, v212
	v_fmamk_f32 v69, v69, 0x3dd53b94, v212
	v_fmamk_f32 v70, v70, 0x3dd53b94, v212
	v_fmamk_f32 v71, v71, 0x3dd53b94, v212
	v_fmamk_f32 v72, v72, 0x3dd53b94, v212
	v_fmamk_f32 v73, v73, 0x3dd53b94, v212
	v_fmamk_f32 v74, v74, 0x3dd53b94, v212
	v_fmamk_f32 v75, v75, 0x3dd53b94, v212
	v_fmamk_f32 v76, v76, 0x3dd53b94, v212
	v_fmamk_f32 v77, v77, 0x3dd53b94, v212
	v_fmamk_f32 v78, v78, 0x3dd53b94, v212
	v_fmamk_f32 v79, v79, 0x3dd53b94, v212
	v_fmamk_f32 v80, v80, 0x3dd53b94, v212
	v_fmac_f32_e32 v212, 0x3dd53b94, v81
	v_exp_f32_e32 v81, v82
	v_exp_f32_e32 v82, v83
	v_exp_f32_e32 v83, v84
	v_exp_f32_e32 v84, v85
	v_exp_f32_e32 v85, v86
	v_exp_f32_e32 v86, v87
	v_exp_f32_e32 v87, v88
	v_exp_f32_e32 v88, v89
	v_exp_f32_e32 v89, v90
	v_exp_f32_e32 v90, v91
	v_exp_f32_e32 v91, v92
	v_exp_f32_e32 v92, v93
	v_exp_f32_e32 v93, v94
	v_exp_f32_e32 v94, v95
	v_exp_f32_e32 v95, v96
	v_exp_f32_e32 v96, v97
	v_exp_f32_e32 v97, v66
	v_add_f32_e32 v66, 0, v81
	v_add_f32_e32 v66, v82, v66
	v_add_f32_e32 v66, v83, v66
	v_add_f32_e32 v66, v84, v66
	v_add_f32_e32 v66, v85, v66
	v_add_f32_e32 v66, v86, v66
	v_add_f32_e32 v66, v87, v66
	v_add_f32_e32 v66, v88, v66
	v_add_f32_e32 v66, v89, v66
	v_add_f32_e32 v66, v90, v66
	v_add_f32_e32 v66, v91, v66
	v_add_f32_e32 v66, v92, v66
	v_add_f32_e32 v66, v93, v66
	v_exp_f32_e32 v233, v67
	v_add_f32_e32 v66, v94, v66
	v_exp_f32_e32 v234, v68
	v_add_f32_e32 v66, v95, v66
	v_exp_f32_e32 v235, v69
	v_add_f32_e32 v66, v96, v66
	v_exp_f32_e32 v236, v70
	v_add_f32_e32 v66, v97, v66
	v_exp_f32_e32 v237, v71
	v_add_f32_e32 v66, v233, v66
	v_exp_f32_e32 v242, v72
	v_add_f32_e32 v66, v234, v66
	v_exp_f32_e32 v243, v73
	v_add_f32_e32 v66, v235, v66
	v_exp_f32_e32 v244, v74
	v_add_f32_e32 v66, v236, v66
	v_exp_f32_e32 v245, v75
	v_add_f32_e32 v66, v237, v66
	v_exp_f32_e32 v246, v76
	v_add_f32_e32 v66, v242, v66
	v_exp_f32_e32 v247, v77
	v_add_f32_e32 v66, v243, v66
	v_exp_f32_e32 v248, v78
	v_add_f32_e32 v66, v244, v66
	v_exp_f32_e32 v249, v79
	v_add_f32_e32 v66, v245, v66
	v_exp_f32_e32 v250, v80
	v_add_f32_e32 v66, v246, v66
	v_exp_f32_e32 v251, v212
	v_add_f32_e32 v66, v247, v66
	v_add_f32_e32 v66, v248, v66
	v_add_f32_e32 v66, v249, v66
	v_add_f32_e32 v66, v250, v66
	v_add_f32_e32 v66, v251, v66
	v_mov_b32_e32 v67, v66
	s_nop 1
	v_permlane32_swap_b32_e32 v66, v67
	v_add_f32_e32 v212, v66, v67
	s_add_i32 s17, s17, 1
	v_fmac_f32_e32 v212, v231, v232
	v_cvt_pk_bf16_f32 v66, v81, v82
	v_cvt_pk_bf16_f32 v67, v83, v84
	v_cvt_pk_bf16_f32 v68, v85, v86
	v_cvt_pk_bf16_f32 v69, v87, v88
	v_cvt_pk_bf16_f32 v70, v89, v90
	v_cvt_pk_bf16_f32 v71, v91, v92
	v_cvt_pk_bf16_f32 v72, v93, v94
	v_cvt_pk_bf16_f32 v73, v95, v96
	v_cvt_pk_bf16_f32 v74, v97, v233
	v_cvt_pk_bf16_f32 v75, v234, v235
	v_cvt_pk_bf16_f32 v76, v236, v237
	v_cvt_pk_bf16_f32 v77, v242, v243
	v_cvt_pk_bf16_f32 v78, v244, v245
	v_cvt_pk_bf16_f32 v79, v246, v247
	v_cvt_pk_bf16_f32 v80, v248, v249
	v_cvt_pk_bf16_f32 v81, v250, v251
	v_permlane32_swap_b32_e32 v66, v68
	v_permlane32_swap_b32_e32 v67, v69
	v_permlane32_swap_b32_e32 v70, v72
	v_permlane32_swap_b32_e32 v71, v73
	v_permlane32_swap_b32_e32 v74, v76
	v_permlane32_swap_b32_e32 v75, v77
	v_permlane32_swap_b32_e32 v78, v80
	v_permlane32_swap_b32_e32 v79, v81
	v_lshl_add_u32 v231, s19, 14, v210
	s_setprio 1
	ds_read_b64_tr_b16 v[82:83], v231 offset:0
	ds_read_b64_tr_b16 v[84:85], v231 offset:0x800
	ds_read_b64_tr_b16 v[86:87], v231 offset:0x1000
	ds_read_b64_tr_b16 v[88:89], v231 offset:0x1800
	ds_read_b64_tr_b16 v[90:91], v231 offset:0x2000
	ds_read_b64_tr_b16 v[92:93], v231 offset:0x2800
	ds_read_b64_tr_b16 v[94:95], v231 offset:0x3000
	ds_read_b64_tr_b16 v[96:97], v231 offset:0x3800
	s_nop 0
	s_waitcnt lgkmcnt(6)
	v_mfma_f32_32x32x16_bf16 v[2:17], v[66:69], v[82:85], v[2:17]
	ds_read_b64_tr_b16 v[82:83], v231 offset:0x200
	ds_read_b64_tr_b16 v[84:85], v231 offset:0xa00
	s_waitcnt lgkmcnt(6)
	v_mfma_f32_32x32x16_bf16 v[2:17], v[70:73], v[86:89], v[2:17]
	ds_read_b64_tr_b16 v[86:87], v231 offset:0x1200
	ds_read_b64_tr_b16 v[88:89], v231 offset:0x1a00
	s_waitcnt lgkmcnt(6)
	v_mfma_f32_32x32x16_bf16 v[2:17], v[74:77], v[90:93], v[2:17]
	ds_read_b64_tr_b16 v[90:91], v231 offset:0x2200
	ds_read_b64_tr_b16 v[92:93], v231 offset:0x2a00
	s_waitcnt lgkmcnt(6)
	v_mfma_f32_32x32x16_bf16 v[2:17], v[78:81], v[94:97], v[2:17]
	ds_read_b64_tr_b16 v[94:95], v231 offset:0x3200
	ds_read_b64_tr_b16 v[96:97], v231 offset:0x3a00
	s_waitcnt lgkmcnt(6)
	v_mfma_f32_32x32x16_bf16 v[50:65], v[66:69], v[82:85], v[50:65]
	ds_read_b64_tr_b16 v[82:83], v231 offset:0x400
	ds_read_b64_tr_b16 v[84:85], v231 offset:0xc00
	s_waitcnt lgkmcnt(6)
	v_mfma_f32_32x32x16_bf16 v[50:65], v[70:73], v[86:89], v[50:65]
	ds_read_b64_tr_b16 v[86:87], v231 offset:0x1400
	ds_read_b64_tr_b16 v[88:89], v231 offset:0x1c00
	s_waitcnt lgkmcnt(6)
	v_mfma_f32_32x32x16_bf16 v[50:65], v[74:77], v[90:93], v[50:65]
	ds_read_b64_tr_b16 v[90:91], v231 offset:0x2400
	ds_read_b64_tr_b16 v[92:93], v231 offset:0x2c00
	s_waitcnt lgkmcnt(6)
	v_mfma_f32_32x32x16_bf16 v[50:65], v[78:81], v[94:97], v[50:65]
	ds_read_b64_tr_b16 v[94:95], v231 offset:0x3400
	ds_read_b64_tr_b16 v[96:97], v231 offset:0x3c00
	s_waitcnt lgkmcnt(6)
	v_mfma_f32_32x32x16_bf16 v[34:49], v[66:69], v[82:85], v[34:49]
	ds_read_b64_tr_b16 v[82:83], v231 offset:0x600
	ds_read_b64_tr_b16 v[84:85], v231 offset:0xe00
	s_waitcnt lgkmcnt(6)
	v_mfma_f32_32x32x16_bf16 v[34:49], v[70:73], v[86:89], v[34:49]
	ds_read_b64_tr_b16 v[86:87], v231 offset:0x1600
	ds_read_b64_tr_b16 v[88:89], v231 offset:0x1e00
	s_waitcnt lgkmcnt(6)
	v_mfma_f32_32x32x16_bf16 v[34:49], v[74:77], v[90:93], v[34:49]
	ds_read_b64_tr_b16 v[90:91], v231 offset:0x2600
	ds_read_b64_tr_b16 v[92:93], v231 offset:0x2e00
	s_waitcnt lgkmcnt(6)
	v_mfma_f32_32x32x16_bf16 v[34:49], v[78:81], v[94:97], v[34:49]
	ds_read_b64_tr_b16 v[94:95], v231 offset:0x3600
	ds_read_b64_tr_b16 v[96:97], v231 offset:0x3e00
	s_waitcnt lgkmcnt(6)
	v_mfma_f32_32x32x16_bf16 v[18:33], v[66:69], v[82:85], v[18:33]
	s_waitcnt lgkmcnt(4)
	v_mfma_f32_32x32x16_bf16 v[18:33], v[70:73], v[86:89], v[18:33]
	s_waitcnt lgkmcnt(2)
	v_mfma_f32_32x32x16_bf16 v[18:33], v[74:77], v[90:93], v[18:33]
	s_waitcnt lgkmcnt(0)
	v_mfma_f32_32x32x16_bf16 v[18:33], v[78:81], v[94:97], v[18:33]
	s_setprio 0
	s_xor_b32 s6, s19, 1
	s_lshl_b32 s7, s6, 14
	s_add_i32 s7, s7, 0
	v_add_u32_e32 v66, s7, v225
	s_lshl_b32 s6, s6, 13
	s_waitcnt vmcnt(4)
	ds_write_b128 v66, v[162:165]
	v_add_u32_e32 v66, s7, v227
	s_add_i32 s7, s7, s6
	s_waitcnt vmcnt(3)
	ds_write_b128 v66, v[154:157]
	v_add_u32_e32 v66, s7, v221
	s_waitcnt vmcnt(2)
	ds_write_b128 v66, v[158:161] offset:32768
	v_add_u32_e32 v66, s7, v223
	s_waitcnt vmcnt(1)
	ds_write_b128 v66, v[146:149] offset:32768
	v_add_u32_e32 v66, s7, v224
	v_lshl_add_u64 v[178:179], v[178:179], 0, s[56:57]
	v_lshl_add_u64 v[180:181], v[180:181], 0, s[56:57]
	v_lshl_add_u64 v[182:183], v[182:183], 0, s[56:57]
	v_lshl_add_u64 v[184:185], v[184:185], 0, s[58:59]
	s_cmp_eq_u32 s17, 31
	v_lshl_add_u64 v[186:187], v[186:187], 0, s[58:59]
	s_waitcnt vmcnt(0)
	ds_write_b128 v66, v[150:153] offset:32768
	s_waitcnt lgkmcnt(0)
	s_barrier
	s_cbranch_scc1 .LBB0_641
	v_mov_b32_e32 v231, v212
	s_branch .LBB0_635
